# barrier leader: own acquire (buffer_inv) moved after the XCD generation bump
# speedup vs baseline: 1.0273x; 1.0052x over previous
; DI unsigned xb_add(unsigned* p, unsigned v) { return __hip_atomic_fetch_add(p, v, __ATOMIC_RELAXED, __HIP_MEMORY_SCOPE_AGENT); }
; DI void xcd_barrier(const XcdBarrier& b, const int gw) {
;     ...
;             __builtin_amdgcn_fence(__ATOMIC_ACQUIRE, "agent");
;             xb_add(&bar[XB_XGEN(b.x)], 1u);
;             asm volatile("s_waitcnt vmcnt(0)" ::: "memory");
.LBB0_177:
	s_or_b64 exec, exec, s[8:9]
	s_mov_b64 s[8:9], exec
	v_mbcnt_lo_u32_b32 v0, s8, 0
	v_mbcnt_hi_u32_b32 v0, s9, v0
	v_cmp_eq_u32_e32 vcc, 0, v0
	s_waitcnt vmcnt(0)
	s_and_saveexec_b64 s[10:11], vcc
	s_cbranch_execz .LBB0_179
	s_bcnt1_i32_b64 s8, s[8:9]
	v_mov_b32_e32 v0, s8
	v_mov_b32_e32 v1, 0x2000
	global_atomic_add v1, v0, s[6:7] offset:1024
.LBB0_179:
	s_or_b64 exec, exec, s[10:11]
	buffer_inv sc1
	s_waitcnt vmcnt(0)
